# SWIGLU GEMM epilogue rewritten with packed-f32 batched sigmoid (row scales loaded up front); attention loop: staggered wave halves, ones/negm register copies removed; numerics unchanged
# speedup vs baseline: 1.0265x; 1.0177x over previous
; #define WAIT_BAR(N) asm volatile("s_waitcnt vmcnt(" #N ") lgkmcnt(0)\n\ts_barrier" ::: "memory")
; #define DMA_K(t, so) do { const char* b_ = (const char*)Kh + (size_t)(t) * (KVBLK * LDK * 2); const unsigned d_ = (unsigned)__builtin_amdgcn_readfirstlane(kdst + (so)); glds16(kof[0], b_, d_); glds16(kof[1], b_, d_ + 8192u); } while (0)
; #define DMA_V(t, so) do { const char* b_ = (const char*)Vh + (size_t)(t) * (KVBLK * LDK * 2); const unsigned d_ = (unsigned)__builtin_amdgcn_readfirstlane(vdst + (so)); glds16(vof[0], b_, d_); glds16(vof[1], b_, d_ + 8192u); } while (0)
; #define WAIT_BAR(N) asm volatile("s_waitcnt vmcnt(" #N ") lgkmcnt(0)\n\ts_barrier" ::: "memory")
; #define DMA_K(t, so) do { const char* b_ = (const char*)K8t + (size_t)(t) * (KVBLK * 256); glds16(kof, b_, (unsigned)__builtin_amdgcn_readfirstlane(kdst + (so))); } while (0)
; #define DMA_V(t, so) do { const char* b_ = (const char*)V8t + (size_t)(t) * 8192; glds16(vof, b_, (unsigned)__builtin_amdgcn_readfirstlane(vdst + (so))); } while (0)
; template <bool FIRST> __device__ __forceinline__ void partialSM8(f32x16& p0, f32x16& p1, float& m_ref, f32x16& negm, float& alpha) {
;     ...
;   const float delta = pmax - POFF8;
;   alpha = 1.f;
;   if (FIRST || !__builtin_expect(__all(delta <= THRL8), 1)) {
;     const float dl = FIRST ? delta : fmaxf(delta, 0.f);
;     m_ref += dl;
;     for (int r = 0; r < 16; ++r) { p0[r] -= dl; p1[r] -= dl; }
;     const float nm = POFF8 - m_ref;
;     for (int r = 0; r < 16; ++r) negm[r] = nm;
;     if (!FIRST) alpha = __builtin_amdgcn_exp2f(-dl);
;   }
;   for (int r = 0; r < 16; ++r) p0[r] = __builtin_amdgcn_exp2f(p0[r]);
; __device__ __forceinline__ void attn_fp8_body(const unsigned char* __restrict__ Q8w, const unsigned char* __restrict__ K8t, const unsigned char* __restrict__ V8t,
;                                               bf16_t* __restrict__ Ob, int seq, char* lds, const int tid) {
;     ...
;   f32x16 pA0, pA1, pB0, pB1; float alA, alB; v8i pa; const int NT = seq / KVBLK;
;   DMA_K(0, 0); DMA_V(0, 0); DMA_K(1, SLOT8);
;   WAIT_BAR(0);
;   DMA_K(2, 2 * SLOT8); DMA_V(1, SLOT8);
;   qkt8(pA0, pA1, KP8(0), qr, negm, r32, hi); partialSM8<true>(pA0, pA1, m_ref, negm, alA);
;   WAIT_BAR(2);
;   int s0 = 0, s1 = SLOT8, s2 = 2 * SLOT8;
;     ...
;   for (int j = 1; j + 1 < NT; j += 2) {
.LBB0_61:
	v_sub_f32_e32 v18, v18, v201
	v_sub_f32_e32 v19, v19, v201
	v_sub_f32_e32 v20, v20, v201
	v_sub_f32_e32 v21, v21, v201
	v_sub_f32_e32 v22, v22, v201
	v_sub_f32_e32 v23, v23, v201
	v_sub_f32_e32 v24, v24, v201
	v_sub_f32_e32 v25, v25, v201
	v_sub_f32_e32 v26, v26, v201
	v_sub_f32_e32 v27, v27, v201
	v_sub_f32_e32 v28, v28, v201
	v_sub_f32_e32 v29, v29, v201
	v_sub_f32_e32 v30, v30, v201
	v_sub_f32_e32 v31, v31, v201
	v_sub_f32_e32 v32, v32, v201
	v_sub_f32_e32 v33, v33, v201
	s_and_b32 s10, s10, 0x3fffffc0
	v_exp_f32_e32 v235, v18
	v_exp_f32_e32 v236, v19
	v_exp_f32_e32 v237, v20
	v_exp_f32_e32 v238, v21
	v_exp_f32_e32 v207, v22
	v_exp_f32_e32 v209, v23
	v_exp_f32_e32 v211, v24
	v_exp_f32_e32 v213, v25
	v_exp_f32_e32 v167, v26
	v_exp_f32_e32 v168, v27
	v_exp_f32_e32 v169, v28
	v_exp_f32_e32 v205, v29
	v_exp_f32_e32 v165, v30
	v_exp_f32_e32 v166, v31
	v_exp_f32_e32 v163, v32
	v_exp_f32_e32 v164, v33
	s_lshl_b32 s10, s10, 2
	s_add_i32 s23, s10, 0
	s_add_i32 s23, s23, 0x10000
	v_sub_f32_e32 v129, v17, v201
	v_sub_f32_e32 v128, v16, v201
	v_sub_f32_e32 v127, v15, v201
	v_sub_f32_e32 v126, v14, v201
	v_sub_f32_e32 v125, v13, v201
	v_sub_f32_e32 v124, v12, v201
	v_sub_f32_e32 v123, v11, v201
	v_sub_f32_e32 v122, v10, v201
	v_sub_f32_e32 v121, v9, v201
	v_sub_f32_e32 v120, v8, v201
	v_sub_f32_e32 v119, v7, v201
	v_sub_f32_e32 v118, v6, v201
	v_sub_f32_e32 v117, v5, v201
	v_sub_f32_e32 v116, v4, v201
	v_sub_f32_e32 v115, v3, v201
	s_andn2_b64 vcc, exec, s[8:9]
	v_sub_f32_e32 v114, v2, v201
	s_cbranch_vccnz .LBB0_77
	s_add_u32 s6, s6, 0x4000
	s_addc_u32 s7, s7, 0
	s_add_u32 s8, s4, 0xc000
	v_mov_b32_e32 v2, 0
	s_mov_b32 s39, 2
	v_lshl_add_u32 v203, v193, 2, s23
	s_addc_u32 s9, s5, 0
	s_movk_i32 s34, 0x4000
	s_movk_i32 s35, 0x2000
	s_mov_b32 s10, 0
	v_mov_b32_e32 v3, v2
	v_mov_b32_e32 v4, v2
	v_mov_b32_e32 v5, v2
	v_mov_b32_e32 v6, v2
	v_mov_b32_e32 v7, v2
	v_mov_b32_e32 v8, v2
	v_mov_b32_e32 v9, v2
	v_mov_b32_e32 v10, v2
	v_mov_b32_e32 v11, v2
	v_mov_b32_e32 v12, v2
	v_mov_b32_e32 v13, v2
	v_mov_b32_e32 v14, v2
	v_mov_b32_e32 v15, v2
	v_mov_b32_e32 v16, v2
	v_mov_b32_e32 v17, v2
	v_mov_b32_e32 v50, v2
	v_mov_b32_e32 v51, v2
	v_mov_b32_e32 v52, v2
	v_mov_b32_e32 v53, v2
	v_mov_b32_e32 v54, v2
	v_mov_b32_e32 v55, v2
	v_mov_b32_e32 v56, v2
	v_mov_b32_e32 v57, v2
	v_mov_b32_e32 v58, v2
	v_mov_b32_e32 v59, v2
	v_mov_b32_e32 v60, v2
	v_mov_b32_e32 v61, v2
	v_mov_b32_e32 v62, v2
	v_mov_b32_e32 v63, v2
	v_mov_b32_e32 v64, v2
	v_mov_b32_e32 v65, v2
	v_mov_b32_e32 v34, v2
	v_mov_b32_e32 v35, v2
	v_mov_b32_e32 v36, v2
	v_mov_b32_e32 v37, v2
	v_mov_b32_e32 v38, v2
	v_mov_b32_e32 v39, v2
	v_mov_b32_e32 v40, v2
	v_mov_b32_e32 v41, v2
	v_mov_b32_e32 v42, v2
	v_mov_b32_e32 v43, v2
	v_mov_b32_e32 v44, v2
	v_mov_b32_e32 v45, v2
	v_mov_b32_e32 v46, v2
	v_mov_b32_e32 v47, v2
	v_mov_b32_e32 v48, v2
	v_mov_b32_e32 v49, v2
	v_mov_b32_e32 v18, v2
	v_mov_b32_e32 v19, v2
	v_mov_b32_e32 v20, v2
	v_mov_b32_e32 v21, v2
	v_mov_b32_e32 v22, v2
	v_mov_b32_e32 v23, v2
	v_mov_b32_e32 v24, v2
	v_mov_b32_e32 v25, v2
	v_mov_b32_e32 v26, v2
	v_mov_b32_e32 v27, v2
	v_mov_b32_e32 v28, v2
	v_mov_b32_e32 v29, v2
	v_mov_b32_e32 v30, v2
	v_mov_b32_e32 v31, v2
	v_mov_b32_e32 v32, v2
	v_mov_b32_e32 v33, v2
	v_mov_b32_e32 v66, v2
	v_mov_b32_e32 v67, v2
	v_mov_b32_e32 v68, v2
	v_mov_b32_e32 v69, v2
	v_mov_b32_e32 v70, v2
	v_mov_b32_e32 v71, v2
	v_mov_b32_e32 v72, v2
	v_mov_b32_e32 v73, v2
	v_mov_b32_e32 v74, v2
	v_mov_b32_e32 v75, v2
	v_mov_b32_e32 v76, v2
	v_mov_b32_e32 v77, v2
	v_mov_b32_e32 v78, v2
	v_mov_b32_e32 v79, v2
	v_mov_b32_e32 v80, v2
	v_mov_b32_e32 v81, v2
	v_mov_b32_e32 v99, v98
	v_mov_b32_e32 v100, v98
	v_mov_b32_e32 v101, v98
	v_mov_b32_e32 v102, v98
	v_mov_b32_e32 v103, v98
	v_mov_b32_e32 v104, v98
	v_mov_b32_e32 v105, v98
	v_mov_b32_e32 v106, v98
	v_mov_b32_e32 v107, v98
	v_mov_b32_e32 v108, v98
	v_mov_b32_e32 v109, v98
	v_mov_b32_e32 v110, v98
	v_mov_b32_e32 v111, v98
	v_mov_b32_e32 v112, v98
	v_mov_b32_e32 v113, v98
	v_mov_b32_e32 v239, v167
	v_mov_b32_e32 v240, v168
	v_mov_b32_e32 v241, v169
	v_mov_b32_e32 v242, v165
	v_mov_b32_e32 v243, v166
	v_mov_b32_e32 v244, v163
	v_mov_b32_e32 v245, v164
	v_mov_b32_e32 v163, v162
	v_mov_b32_e32 v164, v162
	v_mov_b32_e32 v165, v162
	v_mov_b32_e32 v166, v162
	v_mov_b32_e32 v167, v162
	v_mov_b32_e32 v168, v162
	v_mov_b32_e32 v169, v162
	v_readlane_b32 s26, v253, 6
	s_nop 3
	s_cmp_lt_u32 s26, 4
	s_cbranch_scc1 .Lattn_h1_entry
	s_barrier
	s_branch .Lattn_h1_entry
; __device__ __forceinline__ v8i cat8(v4i a, v4i b) { return (v8i){a[0], a[1], a[2], a[3], b[0], b[1], b[2], b[3]}; }
; __device__ __forceinline__ void finishSM8(f32x16& p0, f32x16& p1, v8i& pa) {
;   for (int r = 0; r < 16; ++r) p1[r] = __builtin_amdgcn_exp2f(p1[r]);
; #pragma unroll
;   for (int w = 0; w < 4; ++w) { int x = 0; x = __builtin_amdgcn_cvt_pk_fp8_f32(p0[4 * w], p0[4 * w + 1], x, false); x = __builtin_amdgcn_cvt_pk_fp8_f32(p0[4 * w + 2], p0[4 * w + 3], x, true); pa[w] = x; }
; #pragma unroll
;   for (int w = 0; w < 4; ++w) { int x = 0; x = __builtin_amdgcn_cvt_pk_fp8_f32(p1[4 * w], p1[4 * w + 1], x, false); x = __builtin_amdgcn_cvt_pk_fp8_f32(p1[4 * w + 2], p1[4 * w + 3], x, true); pa[4 + w] = x; }
; }
; __device__ __forceinline__ void qkt8(f32x16& p0, f32x16& p1, const char* Ks, const v8i* qr, const f32x16& negm, int r32, int hi) {
; #pragma unroll
;   for (int c = 0; c < 2; ++c) { const int b0 = 64 * c + 32 * hi;
;     const v8i a0 = cat8(*reinterpret_cast<const v4i*>(Ks + KSW8(r32, b0)), *reinterpret_cast<const v4i*>(Ks + KSW8(r32, b0 + 16)));
;     const v8i a1 = cat8(*reinterpret_cast<const v4i*>(Ks + KSW8(32 + r32, b0)), *reinterpret_cast<const v4i*>(Ks + KSW8(32 + r32, b0 + 16)));
;     if (c == 0) { p0 = __builtin_amdgcn_mfma_scale_f32_32x32x64_f8f6f4(a0, qr[c], negm, 0, 0, 0, 0, 0, 0); p1 = __builtin_amdgcn_mfma_scale_f32_32x32x64_f8f6f4(a1, qr[c], negm, 0, 0, 0, 0, 0, 0); }
;     else { p0 = __builtin_amdgcn_mfma_scale_f32_32x32x64_f8f6f4(a0, qr[c], p0, 0, 0, 0, 0, 0, 0); p1 = __builtin_amdgcn_mfma_scale_f32_32x32x64_f8f6f4(a1, qr[c], p1, 0, 0, 0, 0, 0, 0); } }
; }
; __device__ __forceinline__ void pv8(f32x16* o, const char* Vs, v8i pa, int r32, int hi) {
; #pragma unroll
;   for (int d0 = 0; d0 < 4; ++d0) { const int col = 32 * d0 + r32;
;     const v8i b = cat8(*reinterpret_cast<const v4i*>(Vs + VSW8(col, 32 * hi)), *reinterpret_cast<const v4i*>(Vs + VSW8(col, 32 * hi + 16)));
;     o[d0] = __builtin_amdgcn_mfma_scale_f32_32x32x64_f8f6f4(pa, b, o[d0], 0, 0, 0, 0, 0, 0); }
;   const int one4 = 0x38383838;
;   const v8i ones = (v8i){one4, one4, one4, one4, one4, one4, one4, one4};
;   o[4] = __builtin_amdgcn_mfma_scale_f32_32x32x64_f8f6f4(pa, ones, o[4], 0, 0, 0, 0, 0, 0);
; }
.LBB0_63:
	v_exp_f32_e32 v235, v130
	v_exp_f32_e32 v236, v131
	v_exp_f32_e32 v237, v132
	v_exp_f32_e32 v238, v133
	v_exp_f32_e32 v207, v134
	v_exp_f32_e32 v209, v135
	v_exp_f32_e32 v211, v136
	v_exp_f32_e32 v213, v137
	v_exp_f32_e32 v239, v138
	v_exp_f32_e32 v240, v139
	v_exp_f32_e32 v241, v140
	v_exp_f32_e32 v205, v141
	v_exp_f32_e32 v242, v142
	v_exp_f32_e32 v243, v143
	v_exp_f32_e32 v244, v144
	v_exp_f32_e32 v245, v145
.Lattn_h1_entry:
	s_mov_b32 s49, s35
	s_mov_b32 s35, s10
	s_add_i32 s10, s10, s36
	s_add_i32 s50, s49, 0
	v_add_u32_e32 v90, s50, v219
	ds_read_b128 v[82:85], v90 offset:4096
	v_add_u32_e32 v94, s50, v220
	ds_read_b128 v[86:89], v94 offset:4096
	ds_read_b128 v[90:93], v90
	ds_read_b128 v[94:97], v94
	s_mov_b32 s11, m0
	s_mov_b32 m0, s10
	s_nop 0
	global_load_lds_dwordx4 v199, s[8:9]
	s_mov_b32 m0, s11
	v_exp_f32_e32 v114, v114
	v_exp_f32_e32 v115, v115
	v_exp_f32_e32 v116, v116
	v_exp_f32_e32 v117, v117
	v_exp_f32_e32 v118, v118
	v_exp_f32_e32 v119, v119
	s_waitcnt lgkmcnt(0)
	v_mfma_f32_32x32x64_f8f6f4 v[130:145], v[90:97], v[178:185], v[98:113]
	v_add_u32_e32 v90, s50, v221
	v_add_u32_e32 v94, s50, v222
	v_exp_f32_e32 v120, v120
	v_exp_f32_e32 v121, v121
	v_exp_f32_e32 v122, v122
	v_mfma_f32_32x32x64_f8f6f4 v[146:161], v[82:89], v[178:185], v[98:113]
	ds_read_b128 v[82:85], v90 offset:4096
	ds_read_b128 v[86:89], v94 offset:4096
	ds_read_b128 v[90:93], v90
	ds_read_b128 v[94:97], v94
	v_exp_f32_e32 v123, v123
	v_exp_f32_e32 v124, v124
	v_exp_f32_e32 v125, v125
	v_exp_f32_e32 v126, v126
	s_waitcnt lgkmcnt(0)
	v_mfma_f32_32x32x64_f8f6f4 v[130:145], v[90:97], v[170:177], v[130:145]
	v_exp_f32_e32 v127, v127
	v_exp_f32_e32 v128, v128
	v_exp_f32_e32 v129, v129
	v_mfma_f32_32x32x64_f8f6f4 v[146:161], v[82:89], v[170:177], v[146:161]
	s_waitcnt vmcnt(2) lgkmcnt(0)
	s_barrier
	s_add_i32 s26, s34, s38
	s_mov_b32 s11, m0
	s_mov_b32 m0, s26
	s_nop 0
	global_load_lds_dwordx4 v1, s[6:7]
	s_mov_b32 m0, s11
	s_add_i32 s10, s35, 0
	v_add_u32_e32 v246, s10, v223
	v_add_u32_e32 v247, s10, v224
	ds_read_b128 v[90:93], v246 offset:24576
	ds_read_b128 v[94:97], v247 offset:24576
	ds_read_b128 v[82:85], v246 offset:26624
	ds_read_b128 v[86:89], v247 offset:26624
	v_cvt_pk_fp8_f32 v119, v118, v119
	v_cvt_pk_fp8_f32 v118, v114, v115
	v_cvt_pk_fp8_f32 v119, v120, v121 op_sel:[0,0,1]
	v_cvt_pk_fp8_f32 v118, v116, v117 op_sel:[0,0,1]
	v_cvt_pk_fp8_f32 v120, v122, v123
	v_cvt_pk_fp8_f32 v121, v126, v127
	v_cvt_pk_fp8_f32 v120, v124, v125 op_sel:[0,0,1]
	v_cvt_pk_fp8_f32 v121, v128, v129 op_sel:[0,0,1]
	v_cvt_pk_fp8_f32 v114, v235, v236
	v_cvt_pk_fp8_f32 v115, v207, v209
	v_cvt_pk_fp8_f32 v116, v239, v240
	v_cvt_pk_fp8_f32 v117, v242, v243
	v_cvt_pk_fp8_f32 v114, v237, v238 op_sel:[0,0,1]
	v_cvt_pk_fp8_f32 v115, v211, v213 op_sel:[0,0,1]
	v_cvt_pk_fp8_f32 v116, v241, v205 op_sel:[0,0,1]
	v_cvt_pk_fp8_f32 v117, v244, v245 op_sel:[0,0,1]
	s_waitcnt lgkmcnt(2)
	v_mfma_f32_32x32x64_f8f6f4 v[2:17], v[114:121], v[90:97], v[2:17]
	ds_read_b128 v[90:93], v246 offset:28672
	ds_read_b128 v[94:97], v247 offset:28672
	v_max3_f32 v122, v130, v131, v132
	v_max3_f32 v123, v133, v134, v135
	v_max3_f32 v122, v122, v136, v137
	v_max3_f32 v123, v123, v138, v139
	v_max3_f32 v122, v122, v140, v141
	s_waitcnt lgkmcnt(2)
	v_mfma_f32_32x32x64_f8f6f4 v[50:65], v[114:121], v[82:89], v[50:65]
	ds_read_b128 v[82:85], v246 offset:30720
	ds_read_b128 v[86:89], v247 offset:30720
	v_max3_f32 v123, v123, v142, v143
	v_max3_f32 v122, v122, v144, v145
	v_max3_f32 v123, v123, v146, v147
	v_max3_f32 v122, v122, v148, v149
	v_max3_f32 v123, v123, v150, v151
	s_waitcnt lgkmcnt(2)
	v_mfma_f32_32x32x64_f8f6f4 v[34:49], v[114:121], v[90:97], v[34:49]
	v_max3_f32 v122, v122, v152, v153
	v_max3_f32 v123, v123, v154, v155
	v_max3_f32 v122, v122, v156, v157
	v_max3_f32 v123, v123, v158, v159
	v_max3_f32 v122, v122, v160, v161
	s_waitcnt lgkmcnt(0)
	v_mfma_f32_32x32x64_f8f6f4 v[18:33], v[114:121], v[82:89], v[18:33]
	v_mfma_f32_32x32x64_f8f6f4 v[66:81], v[114:121], v[162:169], v[66:81]
	v_max_f32_e32 v82, v122, v123
	v_mov_b32_e32 v83, v82
	s_nop 1
	v_permlane32_swap_b32_e32 v82, v83
	v_max_f32_e32 v83, v83, v83
	v_max_f32_e32 v82, v82, v82
	v_max_f32_e32 v82, v82, v83
	v_add_f32_e32 v82, -4.0, v82
	v_cmp_ge_f32_e32 vcc, s82, v82
	s_cmp_eq_u64 vcc, exec
	s_cbranch_scc0 .LBB0_75
	v_mov_b32_e32 v114, 1.0
	v_cmp_gt_f32_e32 vcc, 1.0, v114
	s_cbranch_vccz .LBB0_68

; __device__ __forceinline__ v8i cat8(v4i a, v4i b) { return (v8i){a[0], a[1], a[2], a[3], b[0], b[1], b[2], b[3]}; }
; __device__ __forceinline__ void finishSM8(f32x16& p0, f32x16& p1, v8i& pa) {
;   for (int r = 0; r < 16; ++r) p1[r] = __builtin_amdgcn_exp2f(p1[r]);
; #pragma unroll
;   for (int w = 0; w < 4; ++w) { int x = 0; x = __builtin_amdgcn_cvt_pk_fp8_f32(p0[4 * w], p0[4 * w + 1], x, false); x = __builtin_amdgcn_cvt_pk_fp8_f32(p0[4 * w + 2], p0[4 * w + 3], x, true); pa[w] = x; }
; #pragma unroll
;   for (int w = 0; w < 4; ++w) { int x = 0; x = __builtin_amdgcn_cvt_pk_fp8_f32(p1[4 * w], p1[4 * w + 1], x, false); x = __builtin_amdgcn_cvt_pk_fp8_f32(p1[4 * w + 2], p1[4 * w + 3], x, true); pa[4 + w] = x; }
; }
; __device__ __forceinline__ void qkt8(f32x16& p0, f32x16& p1, const char* Ks, const v8i* qr, const f32x16& negm, int r32, int hi) {
; #pragma unroll
;   for (int c = 0; c < 2; ++c) { const int b0 = 64 * c + 32 * hi;
;     const v8i a0 = cat8(*reinterpret_cast<const v4i*>(Ks + KSW8(r32, b0)), *reinterpret_cast<const v4i*>(Ks + KSW8(r32, b0 + 16)));
;     const v8i a1 = cat8(*reinterpret_cast<const v4i*>(Ks + KSW8(32 + r32, b0)), *reinterpret_cast<const v4i*>(Ks + KSW8(32 + r32, b0 + 16)));
;     if (c == 0) { p0 = __builtin_amdgcn_mfma_scale_f32_32x32x64_f8f6f4(a0, qr[c], negm, 0, 0, 0, 0, 0, 0); p1 = __builtin_amdgcn_mfma_scale_f32_32x32x64_f8f6f4(a1, qr[c], negm, 0, 0, 0, 0, 0, 0); }
;     else { p0 = __builtin_amdgcn_mfma_scale_f32_32x32x64_f8f6f4(a0, qr[c], p0, 0, 0, 0, 0, 0, 0); p1 = __builtin_amdgcn_mfma_scale_f32_32x32x64_f8f6f4(a1, qr[c], p1, 0, 0, 0, 0, 0, 0); } }
; }
; __device__ __forceinline__ void pv8(f32x16* o, const char* Vs, v8i pa, int r32, int hi) {
; #pragma unroll
;   for (int d0 = 0; d0 < 4; ++d0) { const int col = 32 * d0 + r32;
;     const v8i b = cat8(*reinterpret_cast<const v4i*>(Vs + VSW8(col, 32 * hi)), *reinterpret_cast<const v4i*>(Vs + VSW8(col, 32 * hi + 16)));
;     o[d0] = __builtin_amdgcn_mfma_scale_f32_32x32x64_f8f6f4(pa, b, o[d0], 0, 0, 0, 0, 0, 0); }
;   const int one4 = 0x38383838;
;   const v8i ones = (v8i){one4, one4, one4, one4, one4, one4, one4, one4};
;   o[4] = __builtin_amdgcn_mfma_scale_f32_32x32x64_f8f6f4(pa, ones, o[4], 0, 0, 0, 0, 0, 0);
; }
.LBB0_68:
	s_add_i32 s39, s39, 2
	s_min_i32 s10, s39, s19
	s_ashr_i32 s11, s10, 31
	s_lshl_b64 s[10:11], s[10:11], 14
	s_add_u32 s10, s4, s10
	s_waitcnt vmcnt(2) lgkmcnt(0)
	s_barrier
	v_add_u32_e32 v114, s34, v219
	ds_read_b128 v[236:239], v114 offset:4096
	v_add_u32_e32 v118, s34, v220
	ds_read_b128 v[240:243], v118 offset:4096
	ds_read_b128 v[114:117], v114
	ds_read_b128 v[118:121], v118
	v_add_u32_e32 v244, s34, v221
	v_add_u32_e32 v248, s34, v222
	s_addc_u32 s11, s5, s11
	s_add_i32 s26, s49, s36
	s_mov_b32 s27, m0
	s_mov_b32 m0, s26
	s_nop 0
	global_load_lds_dwordx4 v199, s[10:11]
	s_mov_b32 m0, s27
	v_exp_f32_e32 v82, v130
	v_exp_f32_e32 v83, v131
	v_exp_f32_e32 v84, v132
	v_exp_f32_e32 v85, v133
	v_exp_f32_e32 v86, v134
	v_exp_f32_e32 v87, v135
	v_exp_f32_e32 v88, v136
	v_exp_f32_e32 v89, v137
	v_exp_f32_e32 v90, v138
	v_exp_f32_e32 v91, v139
	v_exp_f32_e32 v92, v140
	v_exp_f32_e32 v93, v141
	v_exp_f32_e32 v94, v142
	v_exp_f32_e32 v95, v143
	v_exp_f32_e32 v96, v144
	v_exp_f32_e32 v97, v145
	v_exp_f32_e32 v146, v146
	v_exp_f32_e32 v147, v147
	s_waitcnt lgkmcnt(0)
	v_mfma_f32_32x32x64_f8f6f4 v[130:145], v[114:121], v[178:185], v[98:113]
	v_exp_f32_e32 v148, v148
	v_exp_f32_e32 v149, v149
	v_exp_f32_e32 v150, v150
	v_exp_f32_e32 v151, v151
	v_mfma_f32_32x32x64_f8f6f4 v[114:129], v[236:243], v[178:185], v[98:113]
	ds_read_b128 v[236:239], v244 offset:4096
	ds_read_b128 v[240:243], v248 offset:4096
	ds_read_b128 v[244:247], v244
	ds_read_b128 v[248:251], v248
	v_exp_f32_e32 v152, v152
	v_exp_f32_e32 v153, v153
	v_exp_f32_e32 v154, v154
	v_exp_f32_e32 v155, v155
	v_exp_f32_e32 v156, v156
	s_waitcnt lgkmcnt(0)
	v_mfma_f32_32x32x64_f8f6f4 v[130:145], v[244:251], v[170:177], v[130:145]
	v_exp_f32_e32 v157, v157
	v_exp_f32_e32 v158, v158
	v_exp_f32_e32 v159, v159
	v_exp_f32_e32 v160, v160
	v_exp_f32_e32 v161, v161
	v_mfma_f32_32x32x64_f8f6f4 v[114:129], v[236:243], v[170:177], v[114:129]
	s_waitcnt vmcnt(2) lgkmcnt(0)
	s_barrier
	s_add_u32 s10, s6, 0x2000
	s_addc_u32 s11, s7, 0
	s_add_i32 s26, s35, s38
	s_mov_b32 s27, m0
	s_mov_b32 m0, s26
	s_nop 0
	global_load_lds_dwordx4 v1, s[10:11]
	s_mov_b32 m0, s27
	v_add_u32_e32 v244, s50, v223
	v_add_u32_e32 v248, s50, v224
	ds_read_b128 v[244:247], v244 offset:24576
	ds_read_b128 v[248:251], v248 offset:24576
	v_add_u32_e32 v236, s50, v223
	v_add_u32_e32 v240, s50, v224
	ds_read_b128 v[236:239], v236 offset:26624
	ds_read_b128 v[240:243], v240 offset:26624
	v_cvt_pk_fp8_f32 v151, v150, v151
	v_cvt_pk_fp8_f32 v150, v146, v147
	v_cvt_pk_fp8_f32 v151, v152, v153 op_sel:[0,0,1]
	v_cvt_pk_fp8_f32 v150, v148, v149 op_sel:[0,0,1]
	v_cvt_pk_fp8_f32 v152, v154, v155
	v_cvt_pk_fp8_f32 v153, v158, v159
	v_cvt_pk_fp8_f32 v152, v156, v157 op_sel:[0,0,1]
	v_cvt_pk_fp8_f32 v153, v160, v161 op_sel:[0,0,1]
	v_cvt_pk_fp8_f32 v146, v82, v83
	v_cvt_pk_fp8_f32 v147, v86, v87
	v_cvt_pk_fp8_f32 v148, v90, v91
	v_cvt_pk_fp8_f32 v149, v94, v95
	v_cvt_pk_fp8_f32 v146, v84, v85 op_sel:[0,0,1]
	v_cvt_pk_fp8_f32 v147, v88, v89 op_sel:[0,0,1]
	v_cvt_pk_fp8_f32 v148, v92, v93 op_sel:[0,0,1]
	v_cvt_pk_fp8_f32 v149, v96, v97 op_sel:[0,0,1]
	v_add_u32_e32 v156, s50, v223
	v_add_u32_e32 v157, s50, v224
	s_waitcnt lgkmcnt(2)
	v_mfma_f32_32x32x64_f8f6f4 v[2:17], v[146:153], v[244:251], v[2:17]
	ds_read_b128 v[244:247], v156 offset:28672
	ds_read_b128 v[248:251], v157 offset:28672
	v_max3_f32 v154, v130, v131, v132
	v_max3_f32 v155, v133, v134, v135
	v_max3_f32 v154, v154, v136, v137
	v_max3_f32 v155, v155, v138, v139
	v_max3_f32 v154, v154, v140, v141
	s_waitcnt lgkmcnt(2)
	v_mfma_f32_32x32x64_f8f6f4 v[50:65], v[146:153], v[236:243], v[50:65]
	ds_read_b128 v[236:239], v156 offset:30720
	ds_read_b128 v[240:243], v157 offset:30720
	v_max3_f32 v155, v155, v142, v143
	v_max3_f32 v154, v154, v144, v145
	v_max3_f32 v155, v155, v114, v115
	v_max3_f32 v154, v154, v116, v117
	v_max3_f32 v155, v155, v118, v119
	s_waitcnt lgkmcnt(2)
	v_mfma_f32_32x32x64_f8f6f4 v[34:49], v[146:153], v[244:251], v[34:49]
	v_max3_f32 v154, v154, v120, v121
	v_max3_f32 v155, v155, v122, v123
	v_max3_f32 v154, v154, v124, v125
	v_max3_f32 v155, v155, v126, v127
	v_max3_f32 v154, v154, v128, v129
	s_waitcnt lgkmcnt(0)
	v_mfma_f32_32x32x64_f8f6f4 v[18:33], v[146:153], v[236:243], v[18:33]
	v_mfma_f32_32x32x64_f8f6f4 v[66:81], v[146:153], v[162:169], v[66:81]
	v_max_f32_e32 v146, v154, v155
	v_mov_b32_e32 v147, v146
	s_nop 1
	v_permlane32_swap_b32_e32 v146, v147
	v_max_f32_e32 v147, v147, v147
	v_max_f32_e32 v146, v146, v146
	v_max_f32_e32 v146, v146, v147
	v_add_f32_e32 v147, -4.0, v146
	v_cmp_ge_f32_e32 vcc, s82, v147
	s_cmp_eq_u64 vcc, exec
	v_mov_b32_e32 v146, 1.0
	s_cbranch_scc0 .LBB0_76
	v_cmp_gt_f32_e32 vcc, 1.0, v146
	s_cbranch_vccz .LBB0_73

; #define SBAR() __builtin_amdgcn_sched_barrier(0)
; #define WAIT_BAR(N) asm volatile("s_waitcnt vmcnt(" #N ") lgkmcnt(0)\n\ts_barrier" ::: "memory")
; #define RESC(a) do { if (__any((a) < 1.f)) { if (hi == 0) al_l[r32] = (a); asm volatile("s_waitcnt lgkmcnt(0)" ::: "memory"); \
;     for (int d = 0; d < 4; ++d) for (int r = 0; r < 16; ++r) o[d][r] *= al_l[crow(r, hi)]; } } while (0)
; #define WAIT_BAR(N) asm volatile("s_waitcnt vmcnt(" #N ") lgkmcnt(0)\n\ts_barrier" ::: "memory")
; #define RESC(a) do { if (__any((a) < 1.f)) { if (hi == 0) al_l[r32] = (a); asm volatile("s_waitcnt lgkmcnt(0)" ::: "memory"); \
;     for (int d = 0; d < 5; ++d) for (int r = 0; r < 16; ++r) o[d][r] *= al_l[crow(r, hi)]; } } while (0)
; __device__ __forceinline__ void attn_fp8_body(const unsigned char* __restrict__ Q8w, const unsigned char* __restrict__ K8t, const unsigned char* __restrict__ V8t,
;                                               bf16_t* __restrict__ Ob, int seq, char* lds, const int tid) {
;     ...
;   SBAR(); qkt8(pB0, pB1, KP8(s1), qr, negm, r32, hi);
;   finishSM8(pA0, pA1, pa); SBAR();
;   pv8(o, VP8(s0), pa, r32, hi); partialSM8<false>(pB0, pB1, m_ref, negm, alB);
;   RESC(alB);
;   WAIT_BAR(0);
;   finishSM8(pB0, pB1, pa); SBAR();
;   pv8(o, VP8(s1), pa, r32, hi);
.Lattn_exit2:
	v_exp_f32_e32 v235, v130
	v_exp_f32_e32 v236, v131
	v_exp_f32_e32 v237, v132
	v_exp_f32_e32 v238, v133
	v_exp_f32_e32 v207, v134
	v_exp_f32_e32 v209, v135
	v_exp_f32_e32 v211, v136
	v_exp_f32_e32 v213, v137
	v_exp_f32_e32 v167, v138
	v_exp_f32_e32 v168, v139
	v_exp_f32_e32 v169, v140
	v_exp_f32_e32 v205, v141
	v_exp_f32_e32 v165, v142
	v_exp_f32_e32 v166, v143
	v_exp_f32_e32 v163, v144
	v_exp_f32_e32 v164, v145
	v_mov_b64_e32 v[82:83], v[98:99]
	v_mov_b64_e32 v[84:85], v[100:101]
	v_mov_b64_e32 v[86:87], v[102:103]
	v_mov_b64_e32 v[88:89], v[104:105]
	v_mov_b64_e32 v[90:91], v[106:107]
	v_mov_b64_e32 v[92:93], v[108:109]
	v_mov_b64_e32 v[94:95], v[110:111]
	v_mov_b64_e32 v[96:97], v[112:113]
	s_branch .LBB0_78

; __device__ __forceinline__ unsigned cvt_pk_bf16(float lo, float hi) { unsigned r; asm volatile("v_cvt_pk_bf16_f32 %0, %1, %2" : "=v"(r) : "v"(lo), "v"(hi)); return r; }
; __device__ __forceinline__ float sigmoidf_(float x) { return __builtin_amdgcn_rcpf(1.0f + __expf(-x)); }
;     __device__ __forceinline__ float rs_of(int row) const { return __builtin_amdgcn_rsqf(ss_in[row] * (1.0f / DM) + EPS); }
;     __device__ __forceinline__ void operator()(const f32x4 (&acc)[2][2][4][2], const Unit& u, int wr, int wc, int fr, int fq) const {
;     ...
;         if constexpr (mode == M_SWIGLU) {
; #pragma unroll
;             for (int ai = 0; ai < 2; ++ai)
; #pragma unroll
;                 for (int m = 0; m < 4; ++m) {
;                     const int row = row0 + ai * HALF + m * 16;
;                     const float s = ss_in ? rs_of(row) : 1.0f;
;                     u32x4 w; float v[8];
; #pragma unroll
;                     for (int n = 0; n < 2; ++n)
; #pragma unroll
;                         for (int e = 0; e < 4; ++e) { const float a = acc[ai][0][m][n][e] * s, b = acc[ai][1][m][n][e] * s; v[4 * n + e] = a * b * sigmoidf_(a); }
;                     w.x = cvt_pk_bf16(v[0], v[1]); w.y = cvt_pk_bf16(v[2], v[3]); w.z = cvt_pk_bf16(v[4], v[5]); w.w = cvt_pk_bf16(v[6], v[7]);
;                     *(u32x4*)(O0 + (size_t)row * DFF + u.pn * HALF + cw) = w;
;                 }
.LBB0_622:
	v_lshl_add_u32 v130, s35, 8, v137
	v_cndmask_b32_e64 v134, 0, 1, s[44:45]
	v_ashrrev_i32_e32 v131, 31, v130
	v_mov_b32_e32 v132, 1.0
	v_cmp_ne_u32_e64 s[42:43], 1, v134
	s_lshl_b32 s4, s34, 7
	s_ashr_i32 s5, s4, 31
	v_mov_b64_e32 v[176:177], s[48:49]
	v_mad_i64_i32 v[176:177], s[6:7], v130, s68, v[176:177]
	v_lshl_add_u64 v[176:177], s[4:5], 1, v[176:177]
	v_lshl_add_u64 v[176:177], v[176:177], 0, v[186:187]
	v_mov_b32_e32 v172, 0xbfb8aa3b
	v_mov_b32_e32 v174, 1.0
	s_mov_b64 s[4:5], 0x2c000
	s_mov_b64 s[6:7], 0xdc000
	s_andn2_b64 vcc, exec, s[44:45]
	s_cbranch_vccnz .Lswi_noss
	v_mov_b32_e32 v178, v130
	v_lshlrev_b32_e32 v178, 2, v178
	global_load_dword v140, v178, s[52:53]
	v_or_b32_e32 v178, 16, v130
	v_lshlrev_b32_e32 v179, 2, v178
	global_load_dword v142, v179, s[52:53]
	v_or_b32_e32 v178, 32, v130
	v_lshlrev_b32_e32 v178, 2, v178
	global_load_dword v144, v178, s[52:53]
	v_or_b32_e32 v178, 48, v130
	v_lshlrev_b32_e32 v179, 2, v178
	global_load_dword v146, v179, s[52:53]
	v_or_b32_e32 v178, 128, v130
	v_lshlrev_b32_e32 v178, 2, v178
	global_load_dword v148, v178, s[52:53]
	v_or_b32_e32 v178, 144, v130
	v_lshlrev_b32_e32 v179, 2, v178
	global_load_dword v150, v179, s[52:53]
	v_or_b32_e32 v178, 160, v130
	v_lshlrev_b32_e32 v178, 2, v178
	global_load_dword v152, v178, s[52:53]
	v_or_b32_e32 v178, 176, v130
	v_lshlrev_b32_e32 v179, 2, v178
	global_load_dword v154, v179, s[52:53]
	s_waitcnt vmcnt(0)
	v_fmamk_f32 v140, v140, 0x3a000000, v215
	v_fmamk_f32 v142, v142, 0x3a000000, v215
	v_fmamk_f32 v144, v144, 0x3a000000, v215
	v_fmamk_f32 v146, v146, 0x3a000000, v215
	v_fmamk_f32 v148, v148, 0x3a000000, v215
	v_fmamk_f32 v150, v150, 0x3a000000, v215
	v_fmamk_f32 v152, v152, 0x3a000000, v215
	v_fmamk_f32 v154, v154, 0x3a000000, v215
	v_rsq_f32_e32 v140, v140
	v_rsq_f32_e32 v142, v142
	v_rsq_f32_e32 v144, v144
	v_rsq_f32_e32 v146, v146
	v_rsq_f32_e32 v148, v148
	v_rsq_f32_e32 v150, v150
	v_rsq_f32_e32 v152, v152
	v_rsq_f32_e32 v154, v154
.Lswi_noss:
	s_and_b64 vcc, exec, s[42:43]
	s_cbranch_vccnz .Lswi_ns0
	v_pk_mul_f32 v[122:123], v[122:123], v[140:141] op_sel_hi:[1,0]
	v_pk_mul_f32 v[124:125], v[124:125], v[140:141] op_sel_hi:[1,0]
	v_pk_mul_f32 v[118:119], v[118:119], v[140:141] op_sel_hi:[1,0]
	v_pk_mul_f32 v[120:121], v[120:121], v[140:141] op_sel_hi:[1,0]
	v_pk_mul_f32 v[126:127], v[126:127], v[140:141] op_sel_hi:[1,0]
	v_pk_mul_f32 v[128:129], v[128:129], v[140:141] op_sel_hi:[1,0]
	v_pk_mul_f32 v[114:115], v[114:115], v[140:141] op_sel_hi:[1,0]
	v_pk_mul_f32 v[116:117], v[116:117], v[140:141] op_sel_hi:[1,0]
.Lswi_ns0:
	v_pk_mul_f32 v[164:165], v[122:123], v[172:173] op_sel_hi:[1,0]
	v_pk_mul_f32 v[166:167], v[124:125], v[172:173] op_sel_hi:[1,0]
	v_pk_mul_f32 v[168:169], v[118:119], v[172:173] op_sel_hi:[1,0]
	v_pk_mul_f32 v[170:171], v[120:121], v[172:173] op_sel_hi:[1,0]
	v_exp_f32_e32 v164, v164
	v_exp_f32_e32 v165, v165
	v_exp_f32_e32 v166, v166
	v_exp_f32_e32 v167, v167
	v_exp_f32_e32 v168, v168
	v_exp_f32_e32 v169, v169
	v_exp_f32_e32 v170, v170
	v_exp_f32_e32 v171, v171
	v_pk_mul_f32 v[126:127], v[126:127], v[122:123]
	v_pk_mul_f32 v[128:129], v[128:129], v[124:125]
	v_pk_mul_f32 v[114:115], v[114:115], v[118:119]
	v_pk_mul_f32 v[116:117], v[116:117], v[120:121]
	v_pk_add_f32 v[164:165], v[164:165], v[174:175] op_sel_hi:[1,0]
	v_pk_add_f32 v[166:167], v[166:167], v[174:175] op_sel_hi:[1,0]
	v_pk_add_f32 v[168:169], v[168:169], v[174:175] op_sel_hi:[1,0]
	v_pk_add_f32 v[170:171], v[170:171], v[174:175] op_sel_hi:[1,0]
	v_rcp_f32_e32 v164, v164
	v_rcp_f32_e32 v165, v165
	v_rcp_f32_e32 v166, v166
	v_rcp_f32_e32 v167, v167
	v_rcp_f32_e32 v168, v168
	v_rcp_f32_e32 v169, v169
	v_rcp_f32_e32 v170, v170
	v_rcp_f32_e32 v171, v171
	v_mov_b32_e32 v178, v178
	v_pk_mul_f32 v[126:127], v[126:127], v[164:165]
	v_pk_mul_f32 v[128:129], v[128:129], v[166:167]
	v_pk_mul_f32 v[114:115], v[114:115], v[168:169]
	v_pk_mul_f32 v[116:117], v[116:117], v[170:171]
	v_cvt_pk_bf16_f32 v122, v126, v127
	v_cvt_pk_bf16_f32 v123, v128, v129
	v_cvt_pk_bf16_f32 v124, v114, v115
	v_cvt_pk_bf16_f32 v125, v116, v117
	global_store_dwordx4 v[176:177], v[122:125], off
	v_lshl_add_u64 v[176:177], v[176:177], 0, s[4:5]
	s_cbranch_vccnz .Lswi_ns1
	v_pk_mul_f32 v[110:111], v[110:111], v[142:143] op_sel_hi:[1,0]
	v_pk_mul_f32 v[112:113], v[112:113], v[142:143] op_sel_hi:[1,0]
	v_pk_mul_f32 v[102:103], v[102:103], v[142:143] op_sel_hi:[1,0]
	v_pk_mul_f32 v[104:105], v[104:105], v[142:143] op_sel_hi:[1,0]
	v_pk_mul_f32 v[106:107], v[106:107], v[142:143] op_sel_hi:[1,0]
	v_pk_mul_f32 v[108:109], v[108:109], v[142:143] op_sel_hi:[1,0]
	v_pk_mul_f32 v[98:99], v[98:99], v[142:143] op_sel_hi:[1,0]
	v_pk_mul_f32 v[100:101], v[100:101], v[142:143] op_sel_hi:[1,0]
; __device__ __forceinline__ unsigned cvt_pk_bf16(float lo, float hi) { unsigned r; asm volatile("v_cvt_pk_bf16_f32 %0, %1, %2" : "=v"(r) : "v"(lo), "v"(hi)); return r; }
; __device__ __forceinline__ float sigmoidf_(float x) { return __builtin_amdgcn_rcpf(1.0f + __expf(-x)); }
;     __device__ __forceinline__ float rs_of(int row) const { return __builtin_amdgcn_rsqf(ss_in[row] * (1.0f / DM) + EPS); }
;     __device__ __forceinline__ void operator()(const f32x4 (&acc)[2][2][4][2], const Unit& u, int wr, int wc, int fr, int fq) const {
;     ...
;         if constexpr (mode == M_SWIGLU) {
; #pragma unroll
;             for (int ai = 0; ai < 2; ++ai)
; #pragma unroll
;                 for (int m = 0; m < 4; ++m) {
;                     const int row = row0 + ai * HALF + m * 16;
;                     const float s = ss_in ? rs_of(row) : 1.0f;
;                     u32x4 w; float v[8];
; #pragma unroll
;                     for (int n = 0; n < 2; ++n)
; #pragma unroll
;                         for (int e = 0; e < 4; ++e) { const float a = acc[ai][0][m][n][e] * s, b = acc[ai][1][m][n][e] * s; v[4 * n + e] = a * b * sigmoidf_(a); }
;                     w.x = cvt_pk_bf16(v[0], v[1]); w.y = cvt_pk_bf16(v[2], v[3]); w.z = cvt_pk_bf16(v[4], v[5]); w.w = cvt_pk_bf16(v[6], v[7]);
;                     *(u32x4*)(O0 + (size_t)row * DFF + u.pn * HALF + cw) = w;
;                 }
.Lswi_ns1:
	v_pk_mul_f32 v[164:165], v[110:111], v[172:173] op_sel_hi:[1,0]
	v_pk_mul_f32 v[166:167], v[112:113], v[172:173] op_sel_hi:[1,0]
	v_pk_mul_f32 v[168:169], v[102:103], v[172:173] op_sel_hi:[1,0]
	v_pk_mul_f32 v[170:171], v[104:105], v[172:173] op_sel_hi:[1,0]
	v_exp_f32_e32 v164, v164
	v_exp_f32_e32 v165, v165
	v_exp_f32_e32 v166, v166
	v_exp_f32_e32 v167, v167
	v_exp_f32_e32 v168, v168
	v_exp_f32_e32 v169, v169
	v_exp_f32_e32 v170, v170
	v_exp_f32_e32 v171, v171
	v_pk_mul_f32 v[106:107], v[106:107], v[110:111]
	v_pk_mul_f32 v[108:109], v[108:109], v[112:113]
	v_pk_mul_f32 v[98:99], v[98:99], v[102:103]
	v_pk_mul_f32 v[100:101], v[100:101], v[104:105]
	v_pk_add_f32 v[164:165], v[164:165], v[174:175] op_sel_hi:[1,0]
	v_pk_add_f32 v[166:167], v[166:167], v[174:175] op_sel_hi:[1,0]
	v_pk_add_f32 v[168:169], v[168:169], v[174:175] op_sel_hi:[1,0]
	v_pk_add_f32 v[170:171], v[170:171], v[174:175] op_sel_hi:[1,0]
	v_rcp_f32_e32 v164, v164
	v_rcp_f32_e32 v165, v165
	v_rcp_f32_e32 v166, v166
	v_rcp_f32_e32 v167, v167
	v_rcp_f32_e32 v168, v168
	v_rcp_f32_e32 v169, v169
	v_rcp_f32_e32 v170, v170
	v_rcp_f32_e32 v171, v171
	v_mov_b32_e32 v178, v178
	v_pk_mul_f32 v[106:107], v[106:107], v[164:165]
	v_pk_mul_f32 v[108:109], v[108:109], v[166:167]
	v_pk_mul_f32 v[98:99], v[98:99], v[168:169]
	v_pk_mul_f32 v[100:101], v[100:101], v[170:171]
	v_cvt_pk_bf16_f32 v110, v106, v107
	v_cvt_pk_bf16_f32 v111, v108, v109
	v_cvt_pk_bf16_f32 v112, v98, v99
	v_cvt_pk_bf16_f32 v113, v100, v101
	global_store_dwordx4 v[176:177], v[110:113], off
	v_lshl_add_u64 v[176:177], v[176:177], 0, s[4:5]
	s_cbranch_vccnz .Lswi_ns2
	v_pk_mul_f32 v[94:95], v[94:95], v[144:145] op_sel_hi:[1,0]
	v_pk_mul_f32 v[96:97], v[96:97], v[144:145] op_sel_hi:[1,0]
	v_pk_mul_f32 v[86:87], v[86:87], v[144:145] op_sel_hi:[1,0]
	v_pk_mul_f32 v[88:89], v[88:89], v[144:145] op_sel_hi:[1,0]
	v_pk_mul_f32 v[90:91], v[90:91], v[144:145] op_sel_hi:[1,0]
	v_pk_mul_f32 v[92:93], v[92:93], v[144:145] op_sel_hi:[1,0]
	v_pk_mul_f32 v[82:83], v[82:83], v[144:145] op_sel_hi:[1,0]
	v_pk_mul_f32 v[84:85], v[84:85], v[144:145] op_sel_hi:[1,0]
.Lswi_ns2:
	v_pk_mul_f32 v[164:165], v[94:95], v[172:173] op_sel_hi:[1,0]
	v_pk_mul_f32 v[166:167], v[96:97], v[172:173] op_sel_hi:[1,0]
	v_pk_mul_f32 v[168:169], v[86:87], v[172:173] op_sel_hi:[1,0]
	v_pk_mul_f32 v[170:171], v[88:89], v[172:173] op_sel_hi:[1,0]
	v_exp_f32_e32 v164, v164
	v_exp_f32_e32 v165, v165
	v_exp_f32_e32 v166, v166
	v_exp_f32_e32 v167, v167
	v_exp_f32_e32 v168, v168
	v_exp_f32_e32 v169, v169
	v_exp_f32_e32 v170, v170
	v_exp_f32_e32 v171, v171
	v_pk_mul_f32 v[90:91], v[90:91], v[94:95]
	v_pk_mul_f32 v[92:93], v[92:93], v[96:97]
	v_pk_mul_f32 v[82:83], v[82:83], v[86:87]
	v_pk_mul_f32 v[84:85], v[84:85], v[88:89]
	v_pk_add_f32 v[164:165], v[164:165], v[174:175] op_sel_hi:[1,0]
	v_pk_add_f32 v[166:167], v[166:167], v[174:175] op_sel_hi:[1,0]
	v_pk_add_f32 v[168:169], v[168:169], v[174:175] op_sel_hi:[1,0]
	v_pk_add_f32 v[170:171], v[170:171], v[174:175] op_sel_hi:[1,0]
	v_rcp_f32_e32 v164, v164
	v_rcp_f32_e32 v165, v165
	v_rcp_f32_e32 v166, v166
	v_rcp_f32_e32 v167, v167
	v_rcp_f32_e32 v168, v168
	v_rcp_f32_e32 v169, v169
	v_rcp_f32_e32 v170, v170
	v_rcp_f32_e32 v171, v171
	v_mov_b32_e32 v178, v178
	v_pk_mul_f32 v[90:91], v[90:91], v[164:165]
	v_pk_mul_f32 v[92:93], v[92:93], v[166:167]
	v_pk_mul_f32 v[82:83], v[82:83], v[168:169]
	v_pk_mul_f32 v[84:85], v[84:85], v[170:171]
	v_cvt_pk_bf16_f32 v94, v90, v91
	v_cvt_pk_bf16_f32 v95, v92, v93
	v_cvt_pk_bf16_f32 v96, v82, v83
	v_cvt_pk_bf16_f32 v97, v84, v85
	global_store_dwordx4 v[176:177], v[94:97], off
	v_lshl_add_u64 v[176:177], v[176:177], 0, s[4:5]
	s_cbranch_vccnz .Lswi_ns3
	v_pk_mul_f32 v[78:79], v[78:79], v[146:147] op_sel_hi:[1,0]
	v_pk_mul_f32 v[80:81], v[80:81], v[146:147] op_sel_hi:[1,0]
	v_pk_mul_f32 v[70:71], v[70:71], v[146:147] op_sel_hi:[1,0]
	v_pk_mul_f32 v[72:73], v[72:73], v[146:147] op_sel_hi:[1,0]
	v_pk_mul_f32 v[74:75], v[74:75], v[146:147] op_sel_hi:[1,0]
	v_pk_mul_f32 v[76:77], v[76:77], v[146:147] op_sel_hi:[1,0]
	v_pk_mul_f32 v[66:67], v[66:67], v[146:147] op_sel_hi:[1,0]
	v_pk_mul_f32 v[68:69], v[68:69], v[146:147] op_sel_hi:[1,0]
.Lswi_ns3:
	v_pk_mul_f32 v[164:165], v[78:79], v[172:173] op_sel_hi:[1,0]
	v_pk_mul_f32 v[166:167], v[80:81], v[172:173] op_sel_hi:[1,0]
	v_pk_mul_f32 v[168:169], v[70:71], v[172:173] op_sel_hi:[1,0]
	v_pk_mul_f32 v[170:171], v[72:73], v[172:173] op_sel_hi:[1,0]
	v_exp_f32_e32 v164, v164
	v_exp_f32_e32 v165, v165
	v_exp_f32_e32 v166, v166
	v_exp_f32_e32 v167, v167
	v_exp_f32_e32 v168, v168
	v_exp_f32_e32 v169, v169
	v_exp_f32_e32 v170, v170
	v_exp_f32_e32 v171, v171
	v_pk_mul_f32 v[74:75], v[74:75], v[78:79]
	v_pk_mul_f32 v[76:77], v[76:77], v[80:81]
	v_pk_mul_f32 v[66:67], v[66:67], v[70:71]
	v_pk_mul_f32 v[68:69], v[68:69], v[72:73]
	v_pk_add_f32 v[164:165], v[164:165], v[174:175] op_sel_hi:[1,0]
	v_pk_add_f32 v[166:167], v[166:167], v[174:175] op_sel_hi:[1,0]
	v_pk_add_f32 v[168:169], v[168:169], v[174:175] op_sel_hi:[1,0]
	v_pk_add_f32 v[170:171], v[170:171], v[174:175] op_sel_hi:[1,0]
	v_rcp_f32_e32 v164, v164
	v_rcp_f32_e32 v165, v165
	v_rcp_f32_e32 v166, v166
	v_rcp_f32_e32 v167, v167
	v_rcp_f32_e32 v168, v168
	v_rcp_f32_e32 v169, v169
	v_rcp_f32_e32 v170, v170
	v_rcp_f32_e32 v171, v171
	v_mov_b32_e32 v178, v178
	v_pk_mul_f32 v[74:75], v[74:75], v[164:165]
	v_pk_mul_f32 v[76:77], v[76:77], v[166:167]
	v_pk_mul_f32 v[66:67], v[66:67], v[168:169]
	v_pk_mul_f32 v[68:69], v[68:69], v[170:171]
	v_cvt_pk_bf16_f32 v78, v74, v75
	v_cvt_pk_bf16_f32 v79, v76, v77
	v_cvt_pk_bf16_f32 v80, v66, v67
	v_cvt_pk_bf16_f32 v81, v68, v69
	global_store_dwordx4 v[176:177], v[78:81], off
	v_lshl_add_u64 v[176:177], v[176:177], 0, s[6:7]
	s_cbranch_vccnz .Lswi_ns4
	v_pk_mul_f32 v[62:63], v[62:63], v[148:149] op_sel_hi:[1,0]
	v_pk_mul_f32 v[64:65], v[64:65], v[148:149] op_sel_hi:[1,0]
	v_pk_mul_f32 v[54:55], v[54:55], v[148:149] op_sel_hi:[1,0]
	v_pk_mul_f32 v[56:57], v[56:57], v[148:149] op_sel_hi:[1,0]
	v_pk_mul_f32 v[58:59], v[58:59], v[148:149] op_sel_hi:[1,0]
	v_pk_mul_f32 v[60:61], v[60:61], v[148:149] op_sel_hi:[1,0]
	v_pk_mul_f32 v[50:51], v[50:51], v[148:149] op_sel_hi:[1,0]
	v_pk_mul_f32 v[52:53], v[52:53], v[148:149] op_sel_hi:[1,0]
; __device__ __forceinline__ unsigned cvt_pk_bf16(float lo, float hi) { unsigned r; asm volatile("v_cvt_pk_bf16_f32 %0, %1, %2" : "=v"(r) : "v"(lo), "v"(hi)); return r; }
; __device__ __forceinline__ float sigmoidf_(float x) { return __builtin_amdgcn_rcpf(1.0f + __expf(-x)); }
;     __device__ __forceinline__ float rs_of(int row) const { return __builtin_amdgcn_rsqf(ss_in[row] * (1.0f / DM) + EPS); }
;     __device__ __forceinline__ void operator()(const f32x4 (&acc)[2][2][4][2], const Unit& u, int wr, int wc, int fr, int fq) const {
;     ...
;         if constexpr (mode == M_SWIGLU) {
; #pragma unroll
;             for (int ai = 0; ai < 2; ++ai)
; #pragma unroll
;                 for (int m = 0; m < 4; ++m) {
;                     const int row = row0 + ai * HALF + m * 16;
;                     const float s = ss_in ? rs_of(row) : 1.0f;
;                     u32x4 w; float v[8];
; #pragma unroll
;                     for (int n = 0; n < 2; ++n)
; #pragma unroll
;                         for (int e = 0; e < 4; ++e) { const float a = acc[ai][0][m][n][e] * s, b = acc[ai][1][m][n][e] * s; v[4 * n + e] = a * b * sigmoidf_(a); }
;                     w.x = cvt_pk_bf16(v[0], v[1]); w.y = cvt_pk_bf16(v[2], v[3]); w.z = cvt_pk_bf16(v[4], v[5]); w.w = cvt_pk_bf16(v[6], v[7]);
;                     *(u32x4*)(O0 + (size_t)row * DFF + u.pn * HALF + cw) = w;
;                 }
.Lswi_ns4:
	v_pk_mul_f32 v[164:165], v[62:63], v[172:173] op_sel_hi:[1,0]
	v_pk_mul_f32 v[166:167], v[64:65], v[172:173] op_sel_hi:[1,0]
	v_pk_mul_f32 v[168:169], v[54:55], v[172:173] op_sel_hi:[1,0]
	v_pk_mul_f32 v[170:171], v[56:57], v[172:173] op_sel_hi:[1,0]
	v_exp_f32_e32 v164, v164
	v_exp_f32_e32 v165, v165
	v_exp_f32_e32 v166, v166
	v_exp_f32_e32 v167, v167
	v_exp_f32_e32 v168, v168
	v_exp_f32_e32 v169, v169
	v_exp_f32_e32 v170, v170
	v_exp_f32_e32 v171, v171
	v_pk_mul_f32 v[58:59], v[58:59], v[62:63]
	v_pk_mul_f32 v[60:61], v[60:61], v[64:65]
	v_pk_mul_f32 v[50:51], v[50:51], v[54:55]
	v_pk_mul_f32 v[52:53], v[52:53], v[56:57]
	v_pk_add_f32 v[164:165], v[164:165], v[174:175] op_sel_hi:[1,0]
	v_pk_add_f32 v[166:167], v[166:167], v[174:175] op_sel_hi:[1,0]
	v_pk_add_f32 v[168:169], v[168:169], v[174:175] op_sel_hi:[1,0]
	v_pk_add_f32 v[170:171], v[170:171], v[174:175] op_sel_hi:[1,0]
	v_rcp_f32_e32 v164, v164
	v_rcp_f32_e32 v165, v165
	v_rcp_f32_e32 v166, v166
	v_rcp_f32_e32 v167, v167
	v_rcp_f32_e32 v168, v168
	v_rcp_f32_e32 v169, v169
	v_rcp_f32_e32 v170, v170
	v_rcp_f32_e32 v171, v171
	v_mov_b32_e32 v178, v178
	v_pk_mul_f32 v[58:59], v[58:59], v[164:165]
	v_pk_mul_f32 v[60:61], v[60:61], v[166:167]
	v_pk_mul_f32 v[50:51], v[50:51], v[168:169]
	v_pk_mul_f32 v[52:53], v[52:53], v[170:171]
	v_cvt_pk_bf16_f32 v62, v58, v59
	v_cvt_pk_bf16_f32 v63, v60, v61
	v_cvt_pk_bf16_f32 v64, v50, v51
	v_cvt_pk_bf16_f32 v65, v52, v53
	global_store_dwordx4 v[176:177], v[62:65], off
	v_lshl_add_u64 v[176:177], v[176:177], 0, s[4:5]
	s_cbranch_vccnz .Lswi_ns5
	v_pk_mul_f32 v[46:47], v[46:47], v[150:151] op_sel_hi:[1,0]
	v_pk_mul_f32 v[48:49], v[48:49], v[150:151] op_sel_hi:[1,0]
	v_pk_mul_f32 v[38:39], v[38:39], v[150:151] op_sel_hi:[1,0]
	v_pk_mul_f32 v[40:41], v[40:41], v[150:151] op_sel_hi:[1,0]
	v_pk_mul_f32 v[42:43], v[42:43], v[150:151] op_sel_hi:[1,0]
	v_pk_mul_f32 v[44:45], v[44:45], v[150:151] op_sel_hi:[1,0]
	v_pk_mul_f32 v[34:35], v[34:35], v[150:151] op_sel_hi:[1,0]
	v_pk_mul_f32 v[36:37], v[36:37], v[150:151] op_sel_hi:[1,0]
.Lswi_ns5:
	v_pk_mul_f32 v[164:165], v[46:47], v[172:173] op_sel_hi:[1,0]
	v_pk_mul_f32 v[166:167], v[48:49], v[172:173] op_sel_hi:[1,0]
	v_pk_mul_f32 v[168:169], v[38:39], v[172:173] op_sel_hi:[1,0]
	v_pk_mul_f32 v[170:171], v[40:41], v[172:173] op_sel_hi:[1,0]
	v_exp_f32_e32 v164, v164
	v_exp_f32_e32 v165, v165
	v_exp_f32_e32 v166, v166
	v_exp_f32_e32 v167, v167
	v_exp_f32_e32 v168, v168
	v_exp_f32_e32 v169, v169
	v_exp_f32_e32 v170, v170
	v_exp_f32_e32 v171, v171
	v_pk_mul_f32 v[42:43], v[42:43], v[46:47]
	v_pk_mul_f32 v[44:45], v[44:45], v[48:49]
	v_pk_mul_f32 v[34:35], v[34:35], v[38:39]
	v_pk_mul_f32 v[36:37], v[36:37], v[40:41]
	v_pk_add_f32 v[164:165], v[164:165], v[174:175] op_sel_hi:[1,0]
	v_pk_add_f32 v[166:167], v[166:167], v[174:175] op_sel_hi:[1,0]
	v_pk_add_f32 v[168:169], v[168:169], v[174:175] op_sel_hi:[1,0]
	v_pk_add_f32 v[170:171], v[170:171], v[174:175] op_sel_hi:[1,0]
	v_rcp_f32_e32 v164, v164
	v_rcp_f32_e32 v165, v165
	v_rcp_f32_e32 v166, v166
	v_rcp_f32_e32 v167, v167
	v_rcp_f32_e32 v168, v168
	v_rcp_f32_e32 v169, v169
	v_rcp_f32_e32 v170, v170
	v_rcp_f32_e32 v171, v171
	v_mov_b32_e32 v178, v178
	v_pk_mul_f32 v[42:43], v[42:43], v[164:165]
	v_pk_mul_f32 v[44:45], v[44:45], v[166:167]
	v_pk_mul_f32 v[34:35], v[34:35], v[168:169]
	v_pk_mul_f32 v[36:37], v[36:37], v[170:171]
	v_cvt_pk_bf16_f32 v46, v42, v43
	v_cvt_pk_bf16_f32 v47, v44, v45
	v_cvt_pk_bf16_f32 v48, v34, v35
	v_cvt_pk_bf16_f32 v49, v36, v37
	global_store_dwordx4 v[176:177], v[46:49], off
	v_lshl_add_u64 v[176:177], v[176:177], 0, s[4:5]
	s_cbranch_vccnz .Lswi_ns6
	v_pk_mul_f32 v[30:31], v[30:31], v[152:153] op_sel_hi:[1,0]
	v_pk_mul_f32 v[32:33], v[32:33], v[152:153] op_sel_hi:[1,0]
	v_pk_mul_f32 v[22:23], v[22:23], v[152:153] op_sel_hi:[1,0]
	v_pk_mul_f32 v[24:25], v[24:25], v[152:153] op_sel_hi:[1,0]
	v_pk_mul_f32 v[26:27], v[26:27], v[152:153] op_sel_hi:[1,0]
	v_pk_mul_f32 v[28:29], v[28:29], v[152:153] op_sel_hi:[1,0]
	v_pk_mul_f32 v[18:19], v[18:19], v[152:153] op_sel_hi:[1,0]
	v_pk_mul_f32 v[20:21], v[20:21], v[152:153] op_sel_hi:[1,0]
; __device__ __forceinline__ unsigned cvt_pk_bf16(float lo, float hi) { unsigned r; asm volatile("v_cvt_pk_bf16_f32 %0, %1, %2" : "=v"(r) : "v"(lo), "v"(hi)); return r; }
; __device__ __forceinline__ float sigmoidf_(float x) { return __builtin_amdgcn_rcpf(1.0f + __expf(-x)); }
;     __device__ __forceinline__ float rs_of(int row) const { return __builtin_amdgcn_rsqf(ss_in[row] * (1.0f / DM) + EPS); }
; #define PG8_BAR __builtin_amdgcn_s_barrier()
;     __device__ __forceinline__ void operator()(const f32x4 (&acc)[2][2][4][2], const Unit& u, int wr, int wc, int fr, int fq) const {
;     ...
;         if constexpr (mode == M_SWIGLU) {
; #pragma unroll
;             for (int ai = 0; ai < 2; ++ai)
; #pragma unroll
;                 for (int m = 0; m < 4; ++m) {
;                     const int row = row0 + ai * HALF + m * 16;
;                     const float s = ss_in ? rs_of(row) : 1.0f;
;                     u32x4 w; float v[8];
; #pragma unroll
;                     for (int n = 0; n < 2; ++n)
; #pragma unroll
;                         for (int e = 0; e < 4; ++e) { const float a = acc[ai][0][m][n][e] * s, b = acc[ai][1][m][n][e] * s; v[4 * n + e] = a * b * sigmoidf_(a); }
;                     w.x = cvt_pk_bf16(v[0], v[1]); w.y = cvt_pk_bf16(v[2], v[3]); w.z = cvt_pk_bf16(v[4], v[5]); w.w = cvt_pk_bf16(v[6], v[7]);
;                     *(u32x4*)(O0 + (size_t)row * DFF + u.pn * HALF + cw) = w;
;                 }
; template <class Epi> __device__ __forceinline__ void gemm_phase(LAS unsigned char* lds, const Gemm g, const StaticOrder& S, const Epi& E, const int tid) {
;     ...
;         if (wr == 0) PG8_BAR;
;         E(acc, cur, wr, wc, fr, fq);
;         if (!has_next) break;
.Lswi_ns6:
	v_pk_mul_f32 v[164:165], v[30:31], v[172:173] op_sel_hi:[1,0]
	v_pk_mul_f32 v[166:167], v[32:33], v[172:173] op_sel_hi:[1,0]
	v_pk_mul_f32 v[168:169], v[22:23], v[172:173] op_sel_hi:[1,0]
	v_pk_mul_f32 v[170:171], v[24:25], v[172:173] op_sel_hi:[1,0]
	v_exp_f32_e32 v164, v164
	v_exp_f32_e32 v165, v165
	v_exp_f32_e32 v166, v166
	v_exp_f32_e32 v167, v167
	v_exp_f32_e32 v168, v168
	v_exp_f32_e32 v169, v169
	v_exp_f32_e32 v170, v170
	v_exp_f32_e32 v171, v171
	v_pk_mul_f32 v[26:27], v[26:27], v[30:31]
	v_pk_mul_f32 v[28:29], v[28:29], v[32:33]
	v_pk_mul_f32 v[18:19], v[18:19], v[22:23]
	v_pk_mul_f32 v[20:21], v[20:21], v[24:25]
	v_pk_add_f32 v[164:165], v[164:165], v[174:175] op_sel_hi:[1,0]
	v_pk_add_f32 v[166:167], v[166:167], v[174:175] op_sel_hi:[1,0]
	v_pk_add_f32 v[168:169], v[168:169], v[174:175] op_sel_hi:[1,0]
	v_pk_add_f32 v[170:171], v[170:171], v[174:175] op_sel_hi:[1,0]
	v_rcp_f32_e32 v164, v164
	v_rcp_f32_e32 v165, v165
	v_rcp_f32_e32 v166, v166
	v_rcp_f32_e32 v167, v167
	v_rcp_f32_e32 v168, v168
	v_rcp_f32_e32 v169, v169
	v_rcp_f32_e32 v170, v170
	v_rcp_f32_e32 v171, v171
	v_mov_b32_e32 v178, v178
	v_pk_mul_f32 v[26:27], v[26:27], v[164:165]
	v_pk_mul_f32 v[28:29], v[28:29], v[166:167]
	v_pk_mul_f32 v[18:19], v[18:19], v[168:169]
	v_pk_mul_f32 v[20:21], v[20:21], v[170:171]
	v_cvt_pk_bf16_f32 v30, v26, v27
	v_cvt_pk_bf16_f32 v31, v28, v29
	v_cvt_pk_bf16_f32 v32, v18, v19
	v_cvt_pk_bf16_f32 v33, v20, v21
	global_store_dwordx4 v[176:177], v[30:33], off
	v_lshl_add_u64 v[176:177], v[176:177], 0, s[4:5]
	s_cbranch_vccnz .Lswi_ns7
	v_pk_mul_f32 v[14:15], v[14:15], v[154:155] op_sel_hi:[1,0]
	v_pk_mul_f32 v[16:17], v[16:17], v[154:155] op_sel_hi:[1,0]
	v_pk_mul_f32 v[6:7], v[6:7], v[154:155] op_sel_hi:[1,0]
	v_pk_mul_f32 v[8:9], v[8:9], v[154:155] op_sel_hi:[1,0]
	v_pk_mul_f32 v[10:11], v[10:11], v[154:155] op_sel_hi:[1,0]
	v_pk_mul_f32 v[12:13], v[12:13], v[154:155] op_sel_hi:[1,0]
	v_pk_mul_f32 v[2:3], v[2:3], v[154:155] op_sel_hi:[1,0]
	v_pk_mul_f32 v[4:5], v[4:5], v[154:155] op_sel_hi:[1,0]
.Lswi_ns7:
	v_pk_mul_f32 v[164:165], v[14:15], v[172:173] op_sel_hi:[1,0]
	v_pk_mul_f32 v[166:167], v[16:17], v[172:173] op_sel_hi:[1,0]
	v_pk_mul_f32 v[168:169], v[6:7], v[172:173] op_sel_hi:[1,0]
	v_pk_mul_f32 v[170:171], v[8:9], v[172:173] op_sel_hi:[1,0]
	v_exp_f32_e32 v164, v164
	v_exp_f32_e32 v165, v165
	v_exp_f32_e32 v166, v166
	v_exp_f32_e32 v167, v167
	v_exp_f32_e32 v168, v168
	v_exp_f32_e32 v169, v169
	v_exp_f32_e32 v170, v170
	v_exp_f32_e32 v171, v171
	v_pk_mul_f32 v[10:11], v[10:11], v[14:15]
	v_pk_mul_f32 v[12:13], v[12:13], v[16:17]
	v_pk_mul_f32 v[2:3], v[2:3], v[6:7]
	v_pk_mul_f32 v[4:5], v[4:5], v[8:9]
	v_pk_add_f32 v[164:165], v[164:165], v[174:175] op_sel_hi:[1,0]
	v_pk_add_f32 v[166:167], v[166:167], v[174:175] op_sel_hi:[1,0]
	v_pk_add_f32 v[168:169], v[168:169], v[174:175] op_sel_hi:[1,0]
	v_pk_add_f32 v[170:171], v[170:171], v[174:175] op_sel_hi:[1,0]
	v_rcp_f32_e32 v164, v164
	v_rcp_f32_e32 v165, v165
	v_rcp_f32_e32 v166, v166
	v_rcp_f32_e32 v167, v167
	v_rcp_f32_e32 v168, v168
	v_rcp_f32_e32 v169, v169
	v_rcp_f32_e32 v170, v170
	v_rcp_f32_e32 v171, v171
	s_nop 0
	v_pk_mul_f32 v[10:11], v[10:11], v[164:165]
	v_pk_mul_f32 v[12:13], v[12:13], v[166:167]
	v_pk_mul_f32 v[2:3], v[2:3], v[168:169]
	v_pk_mul_f32 v[4:5], v[4:5], v[170:171]
	v_cvt_pk_bf16_f32 v14, v10, v11
	v_cvt_pk_bf16_f32 v15, v12, v13
	v_cvt_pk_bf16_f32 v16, v2, v3
	v_cvt_pk_bf16_f32 v17, v4, v5
	global_store_dwordx4 v[176:177], v[14:17], off
	s_andn2_b64 vcc, exec, s[40:41]
	s_mov_b64 s[4:5], -1
	s_cbranch_vccnz .LBB0_614
	s_andn2_b64 vcc, exec, s[46:47]
	s_cbranch_vccnz .LBB0_613
	s_barrier
	s_branch .LBB0_613
